# GEMM1 rope epilogue: rope tables of row-blocks 1..7 prefetched two blocks ahead into free fragment registers (was 8 serialized load->vmcnt(0) round trips that also waited on the previous block's store
# speedup vs baseline: 1.0106x; 1.0016x over previous
.LBB0_497:
	s_add_u32 s42, s40, 0xfff80080
	s_addc_u32 s43, s41, -1
	s_add_i32 s75, 0, 0x10000
	v_add_u32_e32 v60, s75, v179
	ds_read_b128 v[40:43], v60
	ds_read_b128 v[44:47], v60 offset:1024
	ds_read_b128 v[56:59], v60 offset:2048
	ds_read_b128 v[60:63], v60 offset:3072
	s_cmp_eq_u32 s74, 28
	s_cselect_b32 s53, s47, s43
	s_cselect_b32 s52, s59, s42
	s_cselect_b32 s43, s45, s70
	s_cselect_b32 s42, s60, s61
	v_lshl_add_u64 v[68:69], s[40:41], 0, v[172:173]
	s_add_i32 m0, s19, 0xc000
	ds_read_b128 v[64:67], v181
	ds_read_b128 v[182:185], v181 offset:1024
	ds_read_b128 v[204:207], v181 offset:2048
	ds_read_b128 v[208:211], v181 offset:3072
	ds_read_b128 v[212:215], v181 offset:4096
	ds_read_b128 v[216:219], v181 offset:5120
	ds_read_b128 v[220:223], v181 offset:6144
	ds_read_b128 v[224:227], v181 offset:7168
	global_load_lds_dwordx4 v[68:69], off
	v_lshl_add_u64 v[68:69], s[40:41], 0, v[174:175]
	s_add_i32 m0, s19, 0xe000
	s_nop 0
	global_load_lds_dwordx4 v[68:69], off
	s_waitcnt lgkmcnt(8)
	s_barrier
	s_waitcnt lgkmcnt(0)
	s_setprio 1
	s_waitcnt lgkmcnt(0)
	v_mfma_f32_16x16x32_bf16 v[146:149], v[40:43], v[64:67], v[146:149]
	v_mfma_f32_16x16x32_bf16 v[142:145], v[56:59], v[64:67], v[142:145]
	v_mfma_f32_16x16x32_bf16 v[130:133], v[40:43], v[204:207], v[130:133]
	v_mfma_f32_16x16x32_bf16 v[126:129], v[56:59], v[204:207], v[126:129]
	v_mfma_f32_16x16x32_bf16 v[114:117], v[40:43], v[212:215], v[114:117]
	v_mfma_f32_16x16x32_bf16 v[110:113], v[56:59], v[212:215], v[110:113]
	v_mfma_f32_16x16x32_bf16 v[98:101], v[40:43], v[220:223], v[98:101]
	v_mfma_f32_16x16x32_bf16 v[94:97], v[56:59], v[220:223], v[94:97]
	v_mfma_f32_16x16x32_bf16 v[146:149], v[44:47], v[182:185], v[146:149]
	v_mfma_f32_16x16x32_bf16 v[142:145], v[60:63], v[182:185], v[142:145]
	v_mfma_f32_16x16x32_bf16 v[130:133], v[44:47], v[208:211], v[130:133]
	v_mfma_f32_16x16x32_bf16 v[126:129], v[60:63], v[208:211], v[126:129]
	v_mfma_f32_16x16x32_bf16 v[114:117], v[44:47], v[216:219], v[114:117]
	v_mfma_f32_16x16x32_bf16 v[110:113], v[60:63], v[216:219], v[110:113]
	v_mfma_f32_16x16x32_bf16 v[98:101], v[44:47], v[224:227], v[98:101]
	v_mfma_f32_16x16x32_bf16 v[94:97], v[60:63], v[224:227], v[94:97]
	s_setprio 0
	s_barrier
	s_add_i32 s82, 0, 0x14000
	s_add_i32 s75, s75, s16
	v_add_u32_e32 v68, s82, v179
	v_lshl_add_u64 v[176:177], s[42:43], 0, v[154:155]
	s_mov_b32 m0, s75
	ds_read_b128 v[228:231], v68
	ds_read_b128 v[232:235], v68 offset:1024
	ds_read_b128 v[236:239], v68 offset:2048
	ds_read_b128 v[240:243], v68 offset:3072
	global_load_lds_dwordx4 v[176:177], off
	v_lshl_add_u64 v[186:187], s[42:43], 0, v[150:151]
	s_add_i32 m0, s75, 0x2000
	s_nop 0
	global_load_lds_dwordx4 v[186:187], off
	s_barrier
	s_waitcnt lgkmcnt(0)
	s_setprio 1
	s_waitcnt lgkmcnt(0)
	v_mfma_f32_16x16x32_bf16 v[138:141], v[228:231], v[64:67], v[138:141]
	v_mfma_f32_16x16x32_bf16 v[122:125], v[228:231], v[204:207], v[122:125]
	v_mfma_f32_16x16x32_bf16 v[118:121], v[236:239], v[204:207], v[118:121]
	v_mfma_f32_16x16x32_bf16 v[106:109], v[228:231], v[212:215], v[106:109]
	v_mfma_f32_16x16x32_bf16 v[102:105], v[236:239], v[212:215], v[102:105]
	v_mfma_f32_16x16x32_bf16 v[90:93], v[228:231], v[220:223], v[90:93]
	v_mfma_f32_16x16x32_bf16 v[86:89], v[236:239], v[220:223], v[86:89]
	v_mfma_f32_16x16x32_bf16 v[138:141], v[232:235], v[182:185], v[138:141]
	v_mfma_f32_16x16x32_bf16 v[64:67], v[236:239], v[64:67], v[134:137]
	v_mfma_f32_16x16x32_bf16 v[122:125], v[232:235], v[208:211], v[122:125]
	v_mfma_f32_16x16x32_bf16 v[118:121], v[240:243], v[208:211], v[118:121]
	v_mfma_f32_16x16x32_bf16 v[106:109], v[232:235], v[216:219], v[106:109]
	v_mfma_f32_16x16x32_bf16 v[102:105], v[240:243], v[216:219], v[102:105]
	v_mfma_f32_16x16x32_bf16 v[90:93], v[232:235], v[224:227], v[90:93]
	v_mfma_f32_16x16x32_bf16 v[86:89], v[240:243], v[224:227], v[86:89]
	v_mfma_f32_16x16x32_bf16 v[64:67], v[240:243], v[182:185], v[64:67]
	s_setprio 0
	s_mov_b32 m0, s19
	v_lshl_add_u64 v[244:245], s[52:53], 0, v[156:157]
	s_barrier
	ds_read_b128 v[134:137], v181 offset:16384
	ds_read_b128 v[182:185], v181 offset:17408
	ds_read_b128 v[204:207], v181 offset:18432
	ds_read_b128 v[208:211], v181 offset:19456
	ds_read_b128 v[212:215], v181 offset:20480
	ds_read_b128 v[216:219], v181 offset:21504
	ds_read_b128 v[220:223], v181 offset:22528
	ds_read_b128 v[224:227], v181 offset:23552
	global_load_lds_dwordx4 v[244:245], off
	v_lshl_add_u64 v[246:247], s[52:53], 0, v[152:153]
	s_mov_b32 m0, s20
	s_nop 0
	global_load_lds_dwordx4 v[246:247], off
	s_barrier
	s_waitcnt lgkmcnt(0)
	s_setprio 1
	s_waitcnt lgkmcnt(0)
	v_mfma_f32_16x16x32_bf16 v[82:85], v[40:43], v[134:137], v[82:85]
	v_mfma_f32_16x16x32_bf16 v[78:81], v[56:59], v[134:137], v[78:81]
	v_mfma_f32_16x16x32_bf16 v[52:55], v[40:43], v[204:207], v[52:55]
	v_mfma_f32_16x16x32_bf16 v[48:51], v[56:59], v[204:207], v[48:51]
	v_mfma_f32_16x16x32_bf16 v[28:31], v[40:43], v[212:215], v[28:31]
	v_mfma_f32_16x16x32_bf16 v[24:27], v[56:59], v[212:215], v[24:27]
	v_mfma_f32_16x16x32_bf16 v[12:15], v[40:43], v[220:223], v[12:15]
	v_mfma_f32_16x16x32_bf16 v[8:11], v[56:59], v[220:223], v[8:11]
	v_mfma_f32_16x16x32_bf16 v[82:85], v[44:47], v[182:185], v[82:85]
	v_mfma_f32_16x16x32_bf16 v[78:81], v[60:63], v[182:185], v[78:81]
	v_mfma_f32_16x16x32_bf16 v[52:55], v[44:47], v[208:211], v[52:55]
	v_mfma_f32_16x16x32_bf16 v[48:51], v[60:63], v[208:211], v[48:51]
	v_mfma_f32_16x16x32_bf16 v[28:31], v[44:47], v[216:219], v[28:31]
	v_mfma_f32_16x16x32_bf16 v[24:27], v[60:63], v[216:219], v[24:27]
	v_mfma_f32_16x16x32_bf16 v[12:15], v[44:47], v[224:227], v[12:15]
	v_mfma_f32_16x16x32_bf16 v[8:11], v[60:63], v[224:227], v[8:11]
	s_setprio 0
	s_barrier
	s_add_u32 s80, s42, 0x80000
	s_addc_u32 s81, s43, 0
	s_add_i32 s75, s82, s16
	v_lshl_add_u64 v[40:41], s[80:81], 0, v[154:155]
	s_mov_b32 m0, s75
	s_nop 0
	global_load_lds_dwordx4 v[40:41], off
	v_lshl_add_u64 v[40:41], s[80:81], 0, v[150:151]
	s_add_i32 m0, s75, 0x2000
	s_nop 0
	global_load_lds_dwordx4 v[40:41], off
	s_waitcnt vmcnt(6)
	s_barrier
	s_setprio 1
	v_mfma_f32_16x16x32_bf16 v[36:39], v[228:231], v[204:207], v[36:39]
	v_mfma_f32_16x16x32_bf16 v[32:35], v[236:239], v[204:207], v[32:35]
	v_mfma_f32_16x16x32_bf16 v[20:23], v[228:231], v[212:215], v[20:23]
	v_mfma_f32_16x16x32_bf16 v[16:19], v[236:239], v[212:215], v[16:19]
	v_mfma_f32_16x16x32_bf16 v[4:7], v[228:231], v[220:223], v[4:7]
	v_mfma_f32_16x16x32_bf16 v[0:3], v[236:239], v[220:223], v[0:3]
	v_mfma_f32_16x16x32_bf16 v[40:43], v[228:231], v[134:137], v[74:77]
	v_mfma_f32_16x16x32_bf16 v[44:47], v[236:239], v[134:137], v[70:73]
	v_mfma_f32_16x16x32_bf16 v[36:39], v[232:235], v[208:211], v[36:39]
	v_mfma_f32_16x16x32_bf16 v[32:35], v[240:243], v[208:211], v[32:35]
	v_mfma_f32_16x16x32_bf16 v[20:23], v[232:235], v[216:219], v[20:23]
	v_mfma_f32_16x16x32_bf16 v[16:19], v[240:243], v[216:219], v[16:19]
	v_mfma_f32_16x16x32_bf16 v[4:7], v[232:235], v[224:227], v[4:7]
	v_mfma_f32_16x16x32_bf16 v[0:3], v[240:243], v[224:227], v[0:3]
	v_mfma_f32_16x16x32_bf16 v[40:43], v[232:235], v[182:185], v[40:43]
	v_mfma_f32_16x16x32_bf16 v[44:47], v[240:243], v[182:185], v[44:47]
	s_setprio 0
	s_add_i32 s75, 0, 0x18000
	v_add_u32_e32 v72, s75, v179
	s_barrier
	ds_read_b128 v[56:59], v72
	ds_read_b128 v[60:63], v72 offset:1024
	ds_read_b128 v[68:71], v72 offset:2048
	ds_read_b128 v[72:75], v72 offset:3072
	s_add_u32 s52, s52, 0x80000
	s_addc_u32 s53, s53, 0
	s_mov_b32 m0, s21
	v_lshl_add_u64 v[76:77], s[52:53], 0, v[156:157]
	ds_read_b128 v[134:137], v181 offset:32768
	ds_read_b128 v[182:185], v181 offset:33792
	ds_read_b128 v[204:207], v181 offset:34816
	ds_read_b128 v[208:211], v181 offset:35840
	ds_read_b128 v[212:215], v181 offset:36864
	ds_read_b128 v[216:219], v181 offset:37888
	ds_read_b128 v[220:223], v181 offset:38912
	ds_read_b128 v[224:227], v181 offset:39936
	global_load_lds_dwordx4 v[76:77], off
	v_lshl_add_u64 v[76:77], s[52:53], 0, v[152:153]
	s_mov_b32 m0, s54
	s_nop 0
	global_load_lds_dwordx4 v[76:77], off
	s_waitcnt lgkmcnt(8)
	s_barrier
	s_waitcnt lgkmcnt(0)
	s_setprio 1
	s_waitcnt lgkmcnt(0)
	v_mfma_f32_16x16x32_bf16 v[146:149], v[56:59], v[134:137], v[146:149]
	v_mfma_f32_16x16x32_bf16 v[142:145], v[68:71], v[134:137], v[142:145]
	v_mfma_f32_16x16x32_bf16 v[130:133], v[56:59], v[204:207], v[130:133]
	v_mfma_f32_16x16x32_bf16 v[126:129], v[68:71], v[204:207], v[126:129]
	v_mfma_f32_16x16x32_bf16 v[114:117], v[56:59], v[212:215], v[114:117]
	v_mfma_f32_16x16x32_bf16 v[110:113], v[68:71], v[212:215], v[110:113]
	v_mfma_f32_16x16x32_bf16 v[98:101], v[56:59], v[220:223], v[98:101]
	v_mfma_f32_16x16x32_bf16 v[94:97], v[68:71], v[220:223], v[94:97]
	v_mfma_f32_16x16x32_bf16 v[146:149], v[60:63], v[182:185], v[146:149]
	v_mfma_f32_16x16x32_bf16 v[142:145], v[72:75], v[182:185], v[142:145]
	v_mfma_f32_16x16x32_bf16 v[130:133], v[60:63], v[208:211], v[130:133]
	v_mfma_f32_16x16x32_bf16 v[126:129], v[72:75], v[208:211], v[126:129]
	v_mfma_f32_16x16x32_bf16 v[114:117], v[60:63], v[216:219], v[114:117]
	v_mfma_f32_16x16x32_bf16 v[110:113], v[72:75], v[216:219], v[110:113]
	v_mfma_f32_16x16x32_bf16 v[98:101], v[60:63], v[224:227], v[98:101]
	v_mfma_f32_16x16x32_bf16 v[94:97], v[72:75], v[224:227], v[94:97]
	s_setprio 0
	s_barrier
	s_add_i32 s52, 0, 0x1c000
	v_add_u32_e32 v76, s52, v179
	s_add_i32 s53, s75, s16
	ds_read_b128 v[228:231], v76
	ds_read_b128 v[232:235], v76 offset:1024
	ds_read_b128 v[236:239], v76 offset:2048
	ds_read_b128 v[240:243], v76 offset:3072
	v_lshl_add_u64 v[76:77], v[176:177], 0, s[76:77]
	s_mov_b32 m0, s53
	s_nop 0
	global_load_lds_dwordx4 v[76:77], off
	v_lshl_add_u64 v[76:77], v[186:187], 0, s[76:77]
	s_add_i32 m0, s53, 0x2000
	s_nop 0
	global_load_lds_dwordx4 v[76:77], off
	s_barrier
	s_waitcnt lgkmcnt(0)
	s_setprio 1
	s_waitcnt lgkmcnt(0)
	v_mfma_f32_16x16x32_bf16 v[64:67], v[236:239], v[134:137], v[64:67]
	v_mfma_f32_16x16x32_bf16 v[138:141], v[228:231], v[134:137], v[138:141]
	v_mfma_f32_16x16x32_bf16 v[134:137], v[240:243], v[182:185], v[64:67]
	v_mfma_f32_16x16x32_bf16 v[64:67], v[228:231], v[204:207], v[122:125]
	v_mfma_f32_16x16x32_bf16 v[122:125], v[232:235], v[208:211], v[64:67]
	v_mfma_f32_16x16x32_bf16 v[64:67], v[236:239], v[204:207], v[118:121]
	v_mfma_f32_16x16x32_bf16 v[118:121], v[240:243], v[208:211], v[64:67]
	v_mfma_f32_16x16x32_bf16 v[64:67], v[228:231], v[212:215], v[106:109]
	v_mfma_f32_16x16x32_bf16 v[106:109], v[232:235], v[216:219], v[64:67]
	v_mfma_f32_16x16x32_bf16 v[64:67], v[236:239], v[212:215], v[102:105]
	v_mfma_f32_16x16x32_bf16 v[102:105], v[240:243], v[216:219], v[64:67]
	v_mfma_f32_16x16x32_bf16 v[64:67], v[228:231], v[220:223], v[90:93]
	v_mfma_f32_16x16x32_bf16 v[90:93], v[232:235], v[224:227], v[64:67]
	v_mfma_f32_16x16x32_bf16 v[64:67], v[236:239], v[220:223], v[86:89]
	v_mfma_f32_16x16x32_bf16 v[138:141], v[232:235], v[182:185], v[138:141]
	v_mfma_f32_16x16x32_bf16 v[86:89], v[240:243], v[224:227], v[64:67]
	s_setprio 0
	s_mov_b32 m0, s56
	v_lshl_add_u64 v[76:77], v[244:245], 0, s[76:77]
	s_barrier
	s_nop 1
	ds_read_b128 v[64:67], v181 offset:49152
	ds_read_b128 v[182:185], v181 offset:50176
	ds_read_b128 v[204:207], v181 offset:51200
	ds_read_b128 v[208:211], v181 offset:52224
	ds_read_b128 v[212:215], v181 offset:53248
	ds_read_b128 v[216:219], v181 offset:54272
	ds_read_b128 v[220:223], v181 offset:55296
	ds_read_b128 v[224:227], v181 offset:56320
	global_load_lds_dwordx4 v[76:77], off
	v_lshl_add_u64 v[76:77], v[246:247], 0, s[76:77]
	s_mov_b32 m0, s57
	s_nop 0
	global_load_lds_dwordx4 v[76:77], off
	s_barrier
	s_waitcnt lgkmcnt(0)
	s_setprio 1
	s_waitcnt lgkmcnt(0)
	v_mfma_f32_16x16x32_bf16 v[82:85], v[56:59], v[64:67], v[82:85]
	v_mfma_f32_16x16x32_bf16 v[76:79], v[68:71], v[64:67], v[78:81]
	v_mfma_f32_16x16x32_bf16 v[52:55], v[56:59], v[204:207], v[52:55]
	v_mfma_f32_16x16x32_bf16 v[48:51], v[68:71], v[204:207], v[48:51]
	v_mfma_f32_16x16x32_bf16 v[28:31], v[56:59], v[212:215], v[28:31]
	v_mfma_f32_16x16x32_bf16 v[24:27], v[68:71], v[212:215], v[24:27]
	v_mfma_f32_16x16x32_bf16 v[12:15], v[56:59], v[220:223], v[12:15]
	v_mfma_f32_16x16x32_bf16 v[8:11], v[68:71], v[220:223], v[8:11]
	v_mfma_f32_16x16x32_bf16 v[82:85], v[60:63], v[182:185], v[82:85]
	v_mfma_f32_16x16x32_bf16 v[78:81], v[72:75], v[182:185], v[76:79]
	v_mfma_f32_16x16x32_bf16 v[52:55], v[60:63], v[208:211], v[52:55]
	v_mfma_f32_16x16x32_bf16 v[48:51], v[72:75], v[208:211], v[48:51]
	v_mfma_f32_16x16x32_bf16 v[28:31], v[60:63], v[216:219], v[28:31]
	v_mfma_f32_16x16x32_bf16 v[24:27], v[72:75], v[216:219], v[24:27]
	v_mfma_f32_16x16x32_bf16 v[12:15], v[60:63], v[224:227], v[12:15]
	v_mfma_f32_16x16x32_bf16 v[8:11], v[72:75], v[224:227], v[8:11]
	s_setprio 0
	s_barrier
	s_add_u32 s42, s42, 0x80080
	s_addc_u32 s43, s43, 0
	s_add_i32 s52, s52, s16
	v_lshl_add_u64 v[56:57], s[42:43], 0, v[154:155]
	s_mov_b32 m0, s52
	s_nop 0
	global_load_lds_dwordx4 v[56:57], off
	v_lshl_add_u64 v[56:57], s[42:43], 0, v[150:151]
	s_add_i32 m0, s52, 0x2000
	s_nop 0
	global_load_lds_dwordx4 v[56:57], off
	s_waitcnt vmcnt(6)
	s_barrier
	s_setprio 1
	v_mfma_f32_16x16x32_bf16 v[40:43], v[228:231], v[64:67], v[40:43]
	v_mfma_f32_16x16x32_bf16 v[74:77], v[232:235], v[182:185], v[40:43]
	v_mfma_f32_16x16x32_bf16 v[40:43], v[236:239], v[64:67], v[44:47]
	v_mfma_f32_16x16x32_bf16 v[36:39], v[228:231], v[204:207], v[36:39]
	v_mfma_f32_16x16x32_bf16 v[32:35], v[236:239], v[204:207], v[32:35]
	v_mfma_f32_16x16x32_bf16 v[20:23], v[228:231], v[212:215], v[20:23]
	v_mfma_f32_16x16x32_bf16 v[16:19], v[236:239], v[212:215], v[16:19]
	v_mfma_f32_16x16x32_bf16 v[4:7], v[228:231], v[220:223], v[4:7]
	v_mfma_f32_16x16x32_bf16 v[0:3], v[236:239], v[220:223], v[0:3]
	v_mfma_f32_16x16x32_bf16 v[70:73], v[240:243], v[182:185], v[40:43]
	v_mfma_f32_16x16x32_bf16 v[36:39], v[232:235], v[208:211], v[36:39]
	v_mfma_f32_16x16x32_bf16 v[32:35], v[240:243], v[208:211], v[32:35]
	v_mfma_f32_16x16x32_bf16 v[20:23], v[232:235], v[216:219], v[20:23]
	v_mfma_f32_16x16x32_bf16 v[16:19], v[240:243], v[216:219], v[16:19]
	v_mfma_f32_16x16x32_bf16 v[4:7], v[232:235], v[224:227], v[4:7]
	v_mfma_f32_16x16x32_bf16 v[0:3], v[240:243], v[224:227], v[0:3]
	s_setprio 0
	s_add_i32 s74, s74, 2
	s_add_u32 s40, s40, 0x100
	s_addc_u32 s41, s41, 0
	s_add_u32 s61, s61, 0x100
	s_addc_u32 s70, s70, 0
	s_cmp_gt_u32 s74, 29
	s_barrier
	s_cbranch_scc0 .LBB0_497
	s_ashr_i32 s45, s22, 1
	s_cmp_gt_i32 s23, 15
	s_cselect_b64 s[42:43], -1, 0
	s_add_i32 s40, s45, -5
	s_cmp_lt_u32 s40, 2
	s_cselect_b64 s[40:41], -1, 0
	s_lshl_b32 s23, s23, 8
	s_and_b64 s[52:53], s[42:43], s[40:41]
	s_add_i32 s23, s23, s55
	v_cndmask_b32_e64 v40, 0, 1, s[52:53]
	v_cmp_ne_u32_e64 s[40:41], 1, v40
	s_andn2_b64 vcc, exec, s[52:53]
	v_or_b32_e32 v182, s23, v178
	s_cbranch_vccnz .LBB0_500
	v_lshlrev_b32_e32 v40, 8, v182
	v_and_b32_e32 v160, 0x3cf00, v40
	v_lshl_add_u64 v[40:41], v[158:159], 0, v[160:161]
	global_load_dwordx4 v[44:47], v[40:41], off offset:32
	global_load_dwordx4 v[56:59], v[40:41], off offset:48
	global_load_dwordx4 v[66:69], v[40:41], off
	global_load_dwordx4 v[62:65], v[40:41], off offset:16
	v_or_b32_e32 v248, 16, v182
	v_lshlrev_b32_e32 v248, 8, v248
	v_and_b32_e32 v160, 0x3df00, v248
	v_lshl_add_u64 v[248:249], v[158:159], 0, v[160:161]
	global_load_dwordx4 v[204:207], v[248:249], off offset:16
	global_load_dwordx4 v[208:211], v[248:249], off
	global_load_dwordx4 v[212:215], v[248:249], off offset:48
	global_load_dwordx4 v[216:219], v[248:249], off offset:32
	v_or_b32_e32 v248, 32, v182
	v_lshlrev_b32_e32 v248, 8, v248
	v_and_b32_e32 v160, 0x3ef00, v248
	v_lshl_add_u64 v[248:249], v[158:159], 0, v[160:161]
	global_load_dwordx4 v[220:223], v[248:249], off offset:16
	global_load_dwordx4 v[224:227], v[248:249], off
	global_load_dwordx4 v[228:231], v[248:249], off offset:48
	global_load_dwordx4 v[232:235], v[248:249], off offset:32
	s_waitcnt vmcnt(8)
	v_mov_b32_e32 v40, v44
	v_mov_b32_e32 v41, v46
	v_mov_b32_e32 v46, v45
	v_mov_b32_e32 v44, v56
	v_mov_b32_e32 v45, v58
	v_mov_b32_e32 v58, v57
	v_mov_b32_e32 v56, v66
	v_mov_b32_e32 v57, v68
	v_mov_b32_e32 v68, v67
	v_mov_b32_e32 v60, v62
	v_mov_b32_e32 v61, v64
	v_mov_b32_e32 v64, v63

.LBB0_565:
	s_waitcnt vmcnt(4)
	v_mov_b32_e32 v60, v204
	v_mov_b32_e32 v61, v205
	v_mov_b32_e32 v62, v206
	v_mov_b32_e32 v63, v207
	v_mov_b32_e32 v56, v208
	v_mov_b32_e32 v57, v209
	v_mov_b32_e32 v58, v210
	v_mov_b32_e32 v59, v211
	v_mov_b32_e32 v44, v212
	v_mov_b32_e32 v45, v213
	v_mov_b32_e32 v46, v214
	v_mov_b32_e32 v47, v215
	v_mov_b32_e32 v40, v216
	v_mov_b32_e32 v41, v217
	v_mov_b32_e32 v42, v218
	v_mov_b32_e32 v43, v219
	v_or_b32_e32 v248, 48, v182
	v_lshlrev_b32_e32 v248, 8, v248
	v_and_b32_e32 v160, 0x3ff00, v248
	v_lshl_add_u64 v[248:249], v[158:159], 0, v[160:161]
	global_load_dwordx4 v[204:207], v[248:249], off offset:16
	global_load_dwordx4 v[208:211], v[248:249], off
	global_load_dwordx4 v[212:215], v[248:249], off offset:48
	global_load_dwordx4 v[216:219], v[248:249], off offset:32
	v_mov_b32_e32 v64, v61
	v_mov_b32_e32 v65, v63
	v_mov_b32_e32 v61, v62
	v_mov_b32_e32 v68, v57
	v_mov_b32_e32 v69, v59
	v_mov_b32_e32 v57, v58
	v_mov_b32_e32 v58, v45
	v_mov_b32_e32 v59, v47
	v_mov_b32_e32 v45, v46
	v_mov_b32_e32 v46, v41
	v_mov_b32_e32 v47, v43
	v_mov_b32_e32 v41, v42
	s_and_b64 vcc, exec, s[40:41]
	s_cbranch_vccz .LBB0_509
	s_branch .LBB0_510

.LBB0_567:
	s_waitcnt vmcnt(6)
	v_mov_b32_e32 v60, v220
	v_mov_b32_e32 v61, v221
	v_mov_b32_e32 v62, v222
	v_mov_b32_e32 v63, v223
	v_mov_b32_e32 v56, v224
	v_mov_b32_e32 v57, v225
	v_mov_b32_e32 v58, v226
	v_mov_b32_e32 v59, v227
	v_mov_b32_e32 v44, v228
	v_mov_b32_e32 v45, v229
	v_mov_b32_e32 v46, v230
	v_mov_b32_e32 v47, v231
	v_mov_b32_e32 v40, v232
	v_mov_b32_e32 v41, v233
	v_mov_b32_e32 v42, v234
	v_mov_b32_e32 v43, v235
	v_add_u32_e32 v248, 0x80, v182
	v_lshlrev_b32_e32 v248, 8, v248
	v_and_b32_e32 v160, 0x3cf00, v248
	v_lshl_add_u64 v[248:249], v[158:159], 0, v[160:161]
	global_load_dwordx4 v[220:223], v[248:249], off offset:16
	global_load_dwordx4 v[224:227], v[248:249], off
	global_load_dwordx4 v[228:231], v[248:249], off offset:48
	global_load_dwordx4 v[232:235], v[248:249], off offset:32
	v_mov_b32_e32 v64, v61
	v_mov_b32_e32 v65, v63
	v_mov_b32_e32 v61, v62
	v_mov_b32_e32 v68, v57
	v_mov_b32_e32 v69, v59
	v_mov_b32_e32 v57, v58
	v_mov_b32_e32 v58, v45
	v_mov_b32_e32 v59, v47
	v_mov_b32_e32 v45, v46
	v_mov_b32_e32 v46, v41
	v_mov_b32_e32 v47, v43
	v_mov_b32_e32 v41, v42
	s_and_b64 vcc, exec, s[40:41]
	s_cbranch_vccz .LBB0_517
	s_branch .LBB0_518

.LBB0_569:
	s_waitcnt vmcnt(6)
	v_mov_b32_e32 v60, v204
	v_mov_b32_e32 v61, v205
	v_mov_b32_e32 v62, v206
	v_mov_b32_e32 v63, v207
	v_mov_b32_e32 v56, v208
	v_mov_b32_e32 v57, v209
	v_mov_b32_e32 v58, v210
	v_mov_b32_e32 v59, v211
	v_mov_b32_e32 v44, v212
	v_mov_b32_e32 v45, v213
	v_mov_b32_e32 v46, v214
	v_mov_b32_e32 v47, v215
	v_mov_b32_e32 v40, v216
	v_mov_b32_e32 v41, v217
	v_mov_b32_e32 v42, v218
	v_mov_b32_e32 v43, v219
	v_add_u32_e32 v248, 0x90, v182
	v_lshlrev_b32_e32 v248, 8, v248
	v_and_b32_e32 v160, 0x3df00, v248
	v_lshl_add_u64 v[248:249], v[158:159], 0, v[160:161]
	global_load_dwordx4 v[204:207], v[248:249], off offset:16
	global_load_dwordx4 v[208:211], v[248:249], off
	global_load_dwordx4 v[212:215], v[248:249], off offset:48
	global_load_dwordx4 v[216:219], v[248:249], off offset:32
	v_mov_b32_e32 v64, v61
	v_mov_b32_e32 v65, v63
	v_mov_b32_e32 v61, v62
	v_mov_b32_e32 v68, v57
	v_mov_b32_e32 v69, v59
	v_mov_b32_e32 v57, v58
	v_mov_b32_e32 v58, v45
	v_mov_b32_e32 v59, v47
	v_mov_b32_e32 v45, v46
	v_mov_b32_e32 v46, v41
	v_mov_b32_e32 v47, v43
	v_mov_b32_e32 v41, v42
	s_and_b64 vcc, exec, s[40:41]
	s_cbranch_vccz .LBB0_525
	s_branch .LBB0_526

.LBB0_571:
	s_waitcnt vmcnt(6)
	v_mov_b32_e32 v60, v220
	v_mov_b32_e32 v61, v221
	v_mov_b32_e32 v62, v222
	v_mov_b32_e32 v63, v223
	v_mov_b32_e32 v56, v224
	v_mov_b32_e32 v57, v225
	v_mov_b32_e32 v58, v226
	v_mov_b32_e32 v59, v227
	v_mov_b32_e32 v44, v228
	v_mov_b32_e32 v45, v229
	v_mov_b32_e32 v46, v230
	v_mov_b32_e32 v47, v231
	v_mov_b32_e32 v40, v232
	v_mov_b32_e32 v41, v233
	v_mov_b32_e32 v42, v234
	v_mov_b32_e32 v43, v235
	v_add_u32_e32 v248, 0xa0, v182
	v_lshlrev_b32_e32 v248, 8, v248
	v_and_b32_e32 v160, 0x3ef00, v248
	v_lshl_add_u64 v[248:249], v[158:159], 0, v[160:161]
	global_load_dwordx4 v[220:223], v[248:249], off offset:16
	global_load_dwordx4 v[224:227], v[248:249], off
	global_load_dwordx4 v[228:231], v[248:249], off offset:48
	global_load_dwordx4 v[232:235], v[248:249], off offset:32
	v_mov_b32_e32 v64, v61
	v_mov_b32_e32 v65, v63
	v_mov_b32_e32 v61, v62
	v_mov_b32_e32 v68, v57
	v_mov_b32_e32 v69, v59
	v_mov_b32_e32 v57, v58
	v_mov_b32_e32 v58, v45
	v_mov_b32_e32 v59, v47
	v_mov_b32_e32 v45, v46
	v_mov_b32_e32 v46, v41
	v_mov_b32_e32 v47, v43
	v_mov_b32_e32 v41, v42
	s_and_b64 vcc, exec, s[40:41]
	s_cbranch_vccz .LBB0_533
	s_branch .LBB0_534

.LBB0_573:
	s_waitcnt vmcnt(6)
	v_mov_b32_e32 v60, v204
	v_mov_b32_e32 v61, v205
	v_mov_b32_e32 v62, v206
	v_mov_b32_e32 v63, v207
	v_mov_b32_e32 v56, v208
	v_mov_b32_e32 v57, v209
	v_mov_b32_e32 v58, v210
	v_mov_b32_e32 v59, v211
	v_mov_b32_e32 v44, v212
	v_mov_b32_e32 v45, v213
	v_mov_b32_e32 v46, v214
	v_mov_b32_e32 v47, v215
	v_mov_b32_e32 v40, v216
	v_mov_b32_e32 v41, v217
	v_mov_b32_e32 v42, v218
	v_mov_b32_e32 v43, v219
	v_add_u32_e32 v248, 0xb0, v182
	v_lshlrev_b32_e32 v248, 8, v248
	v_and_b32_e32 v160, 0x3ff00, v248
	v_lshl_add_u64 v[248:249], v[158:159], 0, v[160:161]
	global_load_dwordx4 v[204:207], v[248:249], off offset:16
	global_load_dwordx4 v[208:211], v[248:249], off
	global_load_dwordx4 v[212:215], v[248:249], off offset:48
	global_load_dwordx4 v[216:219], v[248:249], off offset:32
	v_mov_b32_e32 v64, v61
	v_mov_b32_e32 v65, v63
	v_mov_b32_e32 v61, v62
	v_mov_b32_e32 v68, v57
	v_mov_b32_e32 v69, v59
	v_mov_b32_e32 v57, v58
	v_mov_b32_e32 v58, v45
	v_mov_b32_e32 v59, v47
	v_mov_b32_e32 v45, v46
	v_mov_b32_e32 v46, v41
	v_mov_b32_e32 v47, v43
	v_mov_b32_e32 v41, v42
	s_and_b64 vcc, exec, s[40:41]
	s_cbranch_vccz .LBB0_541
	s_branch .LBB0_542

.LBB0_575:
	s_waitcnt vmcnt(6)
	v_mov_b32_e32 v60, v220
	v_mov_b32_e32 v61, v221
	v_mov_b32_e32 v62, v222
	v_mov_b32_e32 v63, v223
	v_mov_b32_e32 v56, v224
	v_mov_b32_e32 v57, v225
	v_mov_b32_e32 v58, v226
	v_mov_b32_e32 v59, v227
	v_mov_b32_e32 v44, v228
	v_mov_b32_e32 v45, v229
	v_mov_b32_e32 v46, v230
	v_mov_b32_e32 v47, v231
	v_mov_b32_e32 v40, v232
	v_mov_b32_e32 v41, v233
	v_mov_b32_e32 v42, v234
	v_mov_b32_e32 v43, v235
	v_mov_b32_e32 v64, v61
	v_mov_b32_e32 v65, v63
	v_mov_b32_e32 v61, v62
	v_mov_b32_e32 v68, v57
	v_mov_b32_e32 v69, v59
	v_mov_b32_e32 v57, v58
	v_mov_b32_e32 v58, v45
	v_mov_b32_e32 v59, v47
	v_mov_b32_e32 v45, v46
	v_mov_b32_e32 v46, v41
	v_mov_b32_e32 v47, v43
	v_mov_b32_e32 v41, v42
	s_and_b64 vcc, exec, s[40:41]
	s_cbranch_vccz .LBB0_549
	s_branch .LBB0_550

.LBB0_577:
	s_waitcnt vmcnt(2)
	v_mov_b32_e32 v60, v204
	v_mov_b32_e32 v61, v205
	v_mov_b32_e32 v62, v206
	v_mov_b32_e32 v63, v207
	v_mov_b32_e32 v56, v208
	v_mov_b32_e32 v57, v209
	v_mov_b32_e32 v58, v210
	v_mov_b32_e32 v59, v211
	v_mov_b32_e32 v44, v212
	v_mov_b32_e32 v45, v213
	v_mov_b32_e32 v46, v214
	v_mov_b32_e32 v47, v215
	v_mov_b32_e32 v40, v216
	v_mov_b32_e32 v41, v217
	v_mov_b32_e32 v42, v218
	v_mov_b32_e32 v43, v219
	v_mov_b32_e32 v64, v61
	v_mov_b32_e32 v65, v63
	v_mov_b32_e32 v61, v62
	v_mov_b32_e32 v68, v57
	v_mov_b32_e32 v69, v59
	v_mov_b32_e32 v57, v58
	v_mov_b32_e32 v58, v45
	v_mov_b32_e32 v59, v47
	v_mov_b32_e32 v45, v46
	v_mov_b32_e32 v46, v41
	v_mov_b32_e32 v47, v43
	v_mov_b32_e32 v41, v42
	s_and_b64 vcc, exec, s[40:41]
	s_cbranch_vccz .LBB0_557
	s_branch .LBB0_558
